# class B: int8 tiles before the LRU summary queue; LRU1_N 864
# baseline (speedup 1.0000x reference)
.LBB0_175:
	s_cmp_eq_u32 s32, 0
	s_cbranch_scc1 .Lp0_done_mode0
	s_waitcnt vmcnt(0) lgkmcnt(0)
	s_barrier
	s_mov_b32 s32, 0
	s_add_i32 s2, s97, 0x70
	s_lshl_b32 s2, s2, 11
	v_lshl_add_u32 v209, v0, 2, s2
	s_add_u32 s2, s76, 0x30c00000
	s_addc_u32 s3, s77, 0
	global_load_dword v210, v209, s[2:3]
	s_add_u32 s2, s2, 0x80000
	s_addc_u32 s3, s3, 0
	global_load_dword v211, v209, s[2:3]
	s_add_u32 s2, s2, 0x80000
	s_addc_u32 s3, s3, 0
	global_load_dword v0, v209, s[2:3]
	s_add_u32 s2, s2, 0x80000
	s_addc_u32 s3, s3, 0
	global_load_dword v1, v209, s[2:3]
	s_add_u32 s2, s2, 0x80000
	s_addc_u32 s3, s3, 0
	global_load_dword v5, v209, s[2:3]
	s_add_u32 s2, s2, 0x80000
	s_addc_u32 s3, s3, 0
	global_load_dword v6, v209, s[2:3]
	s_add_u32 s2, s2, 0x80000
	s_addc_u32 s3, s3, 0
	global_load_dword v8, v209, s[2:3]
	s_add_u32 s2, s2, 0x80000
	s_addc_u32 s3, s3, 0
	global_load_dword v36, v209, s[2:3]
	s_add_u32 s2, s2, 0x80000
	s_addc_u32 s3, s3, 0
	global_load_dword v37, v209, s[2:3]
	s_add_u32 s2, s2, 0x80000
	s_addc_u32 s3, s3, 0
	global_load_dword v38, v209, s[2:3]
	s_add_u32 s2, s2, 0x80000
	s_addc_u32 s3, s3, 0
	global_load_dword v39, v209, s[2:3]
	s_add_u32 s2, s2, 0x80000
	s_addc_u32 s3, s3, 0
	global_load_dword v40, v209, s[2:3]
	s_add_u32 s2, s2, 0x80000
	s_addc_u32 s3, s3, 0
	global_load_dword v41, v209, s[2:3]
	s_add_u32 s2, s2, 0x80000
	s_addc_u32 s3, s3, 0
	global_load_dword v42, v209, s[2:3]
	s_add_u32 s2, s2, 0x80000
	s_addc_u32 s3, s3, 0
	global_load_dword v43, v209, s[2:3]
	s_add_u32 s2, s2, 0x80000
	s_addc_u32 s3, s3, 0
	global_load_dword v44, v209, s[2:3]
	s_add_u32 s2, s2, 0x80000
	s_addc_u32 s3, s3, 0
	global_load_dword v45, v209, s[2:3]
	s_add_u32 s2, s2, 0x80000
	s_addc_u32 s3, s3, 0
	global_load_dword v50, v209, s[2:3]
	s_add_u32 s2, s2, 0x80000
	s_addc_u32 s3, s3, 0
	global_load_dword v51, v209, s[2:3]
	s_add_u32 s2, s2, 0x80000
	s_addc_u32 s3, s3, 0
	global_load_dword v52, v209, s[2:3]
	s_add_u32 s2, s2, 0x80000
	s_addc_u32 s3, s3, 0
	global_load_dword v53, v209, s[2:3]
	s_add_u32 s2, s2, 0x80000
	s_addc_u32 s3, s3, 0
	global_load_dword v54, v209, s[2:3]
	s_add_u32 s2, s2, 0x80000
	s_addc_u32 s3, s3, 0
	global_load_dword v55, v209, s[2:3]
	s_add_u32 s2, s2, 0x80000
	s_addc_u32 s3, s3, 0
	global_load_dword v56, v209, s[2:3]
	s_add_u32 s2, s2, 0x80000
	s_addc_u32 s3, s3, 0
	global_load_dword v57, v209, s[2:3]
	s_add_u32 s2, s2, 0x80000
	s_addc_u32 s3, s3, 0
	global_load_dword v62, v209, s[2:3]
	s_add_u32 s2, s2, 0x80000
	s_addc_u32 s3, s3, 0
	global_load_dword v63, v209, s[2:3]
	s_add_u32 s2, s2, 0x80000
	s_addc_u32 s3, s3, 0
	global_load_dword v64, v209, s[2:3]
	s_add_u32 s2, s2, 0x80000
	s_addc_u32 s3, s3, 0
	global_load_dword v65, v209, s[2:3]
	s_add_u32 s2, s2, 0x80000
	s_addc_u32 s3, s3, 0
	global_load_dword v70, v209, s[2:3]
	s_add_u32 s2, s2, 0x80000
	s_addc_u32 s3, s3, 0
	global_load_dword v71, v209, s[2:3]
	s_add_u32 s2, s2, 0x80000
	s_addc_u32 s3, s3, 0
	global_load_dword v72, v209, s[2:3]
	s_add_u32 s2, s2, 0x80000
	s_addc_u32 s3, s3, 0
	global_load_dword v73, v209, s[2:3]
	s_add_u32 s2, s2, 0x80000
	s_addc_u32 s3, s3, 0
	global_load_dword v82, v209, s[2:3]
	s_add_u32 s2, s2, 0x80000
	s_addc_u32 s3, s3, 0
	global_load_dword v83, v209, s[2:3]
	s_add_u32 s2, s2, 0x80000
	s_addc_u32 s3, s3, 0
	global_load_dword v84, v209, s[2:3]
	s_add_u32 s2, s2, 0x80000
	s_addc_u32 s3, s3, 0
	global_load_dword v85, v209, s[2:3]
	s_add_u32 s2, s2, 0x80000
	s_addc_u32 s3, s3, 0
	global_load_dword v88, v209, s[2:3]
	s_add_u32 s2, s2, 0x80000
	s_addc_u32 s3, s3, 0
	global_load_dword v89, v209, s[2:3]
	s_add_u32 s2, s2, 0x80000
	s_addc_u32 s3, s3, 0
	global_load_dword v94, v209, s[2:3]
	s_add_u32 s2, s2, 0x80000
	s_addc_u32 s3, s3, 0
	global_load_dword v95, v209, s[2:3]
	s_add_u32 s2, s2, 0x80000
	s_addc_u32 s3, s3, 0
	global_load_dword v96, v209, s[2:3]
	s_add_u32 s2, s2, 0x80000
	s_addc_u32 s3, s3, 0
	global_load_dword v97, v209, s[2:3]
	s_add_u32 s2, s2, 0x80000
	s_addc_u32 s3, s3, 0
	global_load_dword v102, v209, s[2:3]
	s_add_u32 s2, s2, 0x80000
	s_addc_u32 s3, s3, 0
	global_load_dword v103, v209, s[2:3]
	s_add_u32 s2, s2, 0x80000
	s_addc_u32 s3, s3, 0
	global_load_dword v104, v209, s[2:3]
	s_add_u32 s2, s2, 0x80000
	s_addc_u32 s3, s3, 0
	global_load_dword v105, v209, s[2:3]
	s_add_u32 s2, s2, 0x80000
	s_addc_u32 s3, s3, 0
	global_load_dword v122, v209, s[2:3]
	s_add_u32 s2, s2, 0x80000
	s_addc_u32 s3, s3, 0
	global_load_dword v123, v209, s[2:3]
	s_add_u32 s2, s2, 0x80000
	s_addc_u32 s3, s3, 0
	global_load_dword v124, v209, s[2:3]
	s_add_u32 s2, s2, 0x80000
	s_addc_u32 s3, s3, 0
	global_load_dword v125, v209, s[2:3]
	s_add_u32 s2, s2, 0x80000
	s_addc_u32 s3, s3, 0
	global_load_dword v170, v209, s[2:3]
	s_add_u32 s2, s2, 0x80000
	s_addc_u32 s3, s3, 0
	global_load_dword v171, v209, s[2:3]
	s_add_u32 s2, s2, 0x80000
	s_addc_u32 s3, s3, 0
	global_load_dword v172, v209, s[2:3]
	s_add_u32 s2, s2, 0x80000
	s_addc_u32 s3, s3, 0
	global_load_dword v173, v209, s[2:3]
	s_add_u32 s2, s2, 0x80000
	s_addc_u32 s3, s3, 0
	global_load_dword v174, v209, s[2:3]
	s_add_u32 s2, s2, 0x80000
	s_addc_u32 s3, s3, 0
	global_load_dword v175, v209, s[2:3]
	s_add_u32 s2, s2, 0x80000
	s_addc_u32 s3, s3, 0
	global_load_dword v195, v209, s[2:3]
	s_add_u32 s2, s2, 0x80000
	s_addc_u32 s3, s3, 0
	global_load_dword v197, v209, s[2:3]
	s_add_u32 s2, s2, 0x80000
	s_addc_u32 s3, s3, 0
	global_load_dword v254, v209, s[2:3]
	s_add_u32 s2, s2, 0x80000
	s_addc_u32 s3, s3, 0
	global_load_dword v255, v209, s[2:3]
	s_waitcnt vmcnt(0)
	v_readlane_b32 s64, v211, 0
	v_readlane_b32 s65, v211, 1
	v_readlane_b32 s66, v211, 2
	v_readlane_b32 s67, v211, 3
	v_readlane_b32 s68, v211, 4
	v_readlane_b32 s69, v211, 5
	v_readlane_b32 s70, v211, 6
	v_readlane_b32 s71, v211, 7
	v_readlane_b32 s72, v211, 8
	v_readlane_b32 s73, v211, 9
	v_readlane_b32 s74, v211, 10
	v_readlane_b32 s75, v211, 11
	v_readlane_b32 s76, v211, 12
	v_readlane_b32 s77, v211, 13
	v_readlane_b32 s78, v211, 14
	v_readlane_b32 s79, v211, 15
	v_readlane_b32 s80, v211, 16
	v_readlane_b32 s81, v211, 17
	v_readlane_b32 s82, v211, 18
	v_readlane_b32 s83, v211, 19
	v_readlane_b32 s84, v211, 20
	v_readlane_b32 s85, v211, 21
	v_readlane_b32 s86, v211, 22
	v_readlane_b32 s87, v211, 23
	v_readlane_b32 s88, v211, 24
	v_readlane_b32 s89, v211, 25
	v_readlane_b32 s90, v211, 26
	v_readlane_b32 s91, v211, 27
	v_readlane_b32 s92, v211, 28
	v_readlane_b32 s93, v211, 29
	v_readlane_b32 s94, v211, 30
	v_readlane_b32 s95, v211, 31
	v_readlane_b32 s96, v211, 32
	v_readlane_b32 s97, v211, 33
	v_readlane_b32 s0, v210, 0
	v_readlane_b32 s1, v210, 1
	v_readlane_b32 s2, v210, 2
	v_readlane_b32 s3, v210, 3
	v_readlane_b32 s4, v210, 4
	v_readlane_b32 s5, v210, 5
	v_readlane_b32 s6, v210, 6
	v_readlane_b32 s7, v210, 7
	v_readlane_b32 s8, v210, 8
	v_readlane_b32 s9, v210, 9
	v_readlane_b32 s10, v210, 10
	v_readlane_b32 s11, v210, 11
	v_readlane_b32 s12, v210, 12
	v_readlane_b32 s13, v210, 13
	v_readlane_b32 s14, v210, 14
	v_readlane_b32 s15, v210, 15
	v_readlane_b32 s16, v210, 16
	v_readlane_b32 s17, v210, 17
	v_readlane_b32 s18, v210, 18
	v_readlane_b32 s19, v210, 19
	v_readlane_b32 s20, v210, 20
	v_readlane_b32 s21, v210, 21
	v_readlane_b32 s22, v210, 22
	v_readlane_b32 s23, v210, 23
	v_readlane_b32 s24, v210, 24
	v_readlane_b32 s25, v210, 25
	v_readlane_b32 s26, v210, 26
	v_readlane_b32 s27, v210, 27
	v_readlane_b32 s28, v210, 28
	v_readlane_b32 s29, v210, 29
	v_readlane_b32 s30, v210, 30
	v_readlane_b32 s31, v210, 31
	v_readlane_b32 s33, v210, 33
	v_readlane_b32 s34, v210, 34
	v_readlane_b32 s35, v210, 35
	v_readlane_b32 s36, v210, 36
	v_readlane_b32 s37, v210, 37
	v_readlane_b32 s38, v210, 38
	v_readlane_b32 s39, v210, 39
	v_readlane_b32 s40, v210, 40
	v_readlane_b32 s41, v210, 41
	v_readlane_b32 s42, v210, 42
	v_readlane_b32 s43, v210, 43
	v_readlane_b32 s44, v210, 44
	v_readlane_b32 s45, v210, 45
	v_readlane_b32 s46, v210, 46
	v_readlane_b32 s47, v210, 47
	v_readlane_b32 s48, v210, 48
	v_readlane_b32 s49, v210, 49
	v_readlane_b32 s50, v210, 50
	v_readlane_b32 s51, v210, 51
	v_readlane_b32 s52, v210, 52
	v_readlane_b32 s53, v210, 53
	v_readlane_b32 s54, v210, 54
	v_readlane_b32 s55, v210, 55
	v_readlane_b32 s56, v210, 56
	v_readlane_b32 s57, v210, 57
	v_readlane_b32 s58, v210, 58
	v_readlane_b32 s59, v210, 59
	v_readlane_b32 s60, v210, 60
	v_readlane_b32 s61, v210, 61
	v_readlane_b32 s62, v210, 62
	v_readlane_b32 s63, v210, 63
	s_mov_b32 s32, 2
	s_nop 4
	s_branch .LBB0_361

.LBB0_636:
	s_cmp_eq_u32 s32, 2
	s_cbranch_scc1 .LBB0_738
	s_mov_b64 s[0:1], exec
	v_readlane_b32 s2, v254, 17
	v_readlane_b32 s3, v254, 18
	s_and_b64 s[2:3], s[0:1], s[2:3]
	s_mov_b64 exec, s[2:3]
	s_cbranch_execz .LBB0_649
	v_mov_b32_e32 v2, 0
	global_load_dword v3, v2, s[76:77] offset:256 sc1
	s_waitcnt vmcnt(0)
	v_cmp_le_u32_e32 vcc, s96, v3
	s_cbranch_vccnz .LBB0_648
	s_mov_b32 s8, 1
	s_branch .LBB0_640

.LBB0_657:
	s_mov_b64 s[14:15], exec
	v_readlane_b32 s16, v254, 17
	v_readlane_b32 s17, v254, 18
	s_and_b64 s[16:17], s[14:15], s[16:17]
	s_mov_b64 exec, s[16:17]
	v_mov_b32_e32 v2, s42
	ds_write_b32 v2, v161
	s_or_b64 exec, exec, s[14:15]
	s_waitcnt lgkmcnt(0)
	s_barrier
	ds_read_b32 v2, v169
	s_movk_i32 s14, 0x35f
	s_waitcnt lgkmcnt(0)
	v_cmp_lt_i32_e64 s[14:15], s14, v2
	v_readfirstlane_b32 s34, v2
	s_and_b64 vcc, exec, s[14:15]
	s_cbranch_vccnz .LBB0_656
	s_mov_b64 s[16:17], exec
	v_readlane_b32 s18, v254, 17
	v_readlane_b32 s19, v254, 18
	s_and_b64 s[18:19], s[16:17], s[18:19]
	s_mov_b64 exec, s[18:19]
	s_cbranch_execz .LBB0_664
	s_mov_b64 s[20:21], exec
	v_mbcnt_lo_u32_b32 v2, s20, 0
	v_mbcnt_hi_u32_b32 v2, s21, v2
	v_cmp_eq_u32_e32 vcc, 0, v2
	s_and_saveexec_b64 s[18:19], vcc
	s_cbranch_execz .LBB0_663
	s_bcnt1_i32_b64 s20, s[20:21]
	v_mov_b32_e32 v3, s20
	global_atomic_add v3, v147, v3, s[76:77] offset:512 sc0

.LBB0_738:
	s_cmp_eq_u32 s32, 3
	s_cbranch_scc0 .Lq_cont
	s_mov_b32 s32, 0
	s_branch .LBB0_1015

.LBB0_1015:
	s_cmp_eq_u32 s32, 2
	s_cbranch_scc0 .Lr_cont
	s_mov_b32 s32, 3
	s_lshl_b32 s2, s97, 11
	v_lshl_add_u32 v4, v0, 2, s2
	s_add_u32 s2, s76, 0x30c00000
	s_addc_u32 s3, s77, 0
	global_load_dword v2, v4, s[2:3]
	s_add_u32 s2, s2, 0x80000
	s_addc_u32 s3, s3, 0
	global_load_dword v3, v4, s[2:3]
	s_add_u32 s2, s2, 0x80000
	s_addc_u32 s3, s3, 0
	s_add_u32 s2, s2, 0x80000
	s_addc_u32 s3, s3, 0
	s_add_u32 s2, s2, 0x80000
	s_addc_u32 s3, s3, 0
	s_add_u32 s2, s2, 0x80000
	s_addc_u32 s3, s3, 0
	s_add_u32 s2, s2, 0x80000
	s_addc_u32 s3, s3, 0
	s_add_u32 s2, s2, 0x80000
	s_addc_u32 s3, s3, 0
	s_add_u32 s2, s2, 0x80000
	s_addc_u32 s3, s3, 0
	s_add_u32 s2, s2, 0x80000
	s_addc_u32 s3, s3, 0
	s_add_u32 s2, s2, 0x80000
	s_addc_u32 s3, s3, 0
	s_add_u32 s2, s2, 0x80000
	s_addc_u32 s3, s3, 0
	s_add_u32 s2, s2, 0x80000
	s_addc_u32 s3, s3, 0
	s_add_u32 s2, s2, 0x80000
	s_addc_u32 s3, s3, 0
	s_add_u32 s2, s2, 0x80000
	s_addc_u32 s3, s3, 0
	s_add_u32 s2, s2, 0x80000
	s_addc_u32 s3, s3, 0
	s_add_u32 s2, s2, 0x80000
	s_addc_u32 s3, s3, 0
	s_add_u32 s2, s2, 0x80000
	s_addc_u32 s3, s3, 0
	s_add_u32 s2, s2, 0x80000
	s_addc_u32 s3, s3, 0
	s_add_u32 s2, s2, 0x80000
	s_addc_u32 s3, s3, 0
	s_add_u32 s2, s2, 0x80000
	s_addc_u32 s3, s3, 0
	s_add_u32 s2, s2, 0x80000
	s_addc_u32 s3, s3, 0
	s_add_u32 s2, s2, 0x80000
	s_addc_u32 s3, s3, 0
	s_add_u32 s2, s2, 0x80000
	s_addc_u32 s3, s3, 0
	s_add_u32 s2, s2, 0x80000
	s_addc_u32 s3, s3, 0
	s_add_u32 s2, s2, 0x80000
	s_addc_u32 s3, s3, 0
	s_add_u32 s2, s2, 0x80000
	s_addc_u32 s3, s3, 0
	s_add_u32 s2, s2, 0x80000
	s_addc_u32 s3, s3, 0
	s_add_u32 s2, s2, 0x80000
	s_addc_u32 s3, s3, 0
	s_add_u32 s2, s2, 0x80000
	s_addc_u32 s3, s3, 0
	s_add_u32 s2, s2, 0x80000
	s_addc_u32 s3, s3, 0
	s_add_u32 s2, s2, 0x80000
	s_addc_u32 s3, s3, 0
	s_add_u32 s2, s2, 0x80000
	s_addc_u32 s3, s3, 0
	s_add_u32 s2, s2, 0x80000
	s_addc_u32 s3, s3, 0
	s_add_u32 s2, s2, 0x80000
	s_addc_u32 s3, s3, 0
	s_add_u32 s2, s2, 0x80000
	s_addc_u32 s3, s3, 0
	s_add_u32 s2, s2, 0x80000
	s_addc_u32 s3, s3, 0
	s_add_u32 s2, s2, 0x80000
	s_addc_u32 s3, s3, 0
	s_add_u32 s2, s2, 0x80000
	s_addc_u32 s3, s3, 0
	s_add_u32 s2, s2, 0x80000
	s_addc_u32 s3, s3, 0
	s_add_u32 s2, s2, 0x80000
	s_addc_u32 s3, s3, 0
	s_add_u32 s2, s2, 0x80000
	s_addc_u32 s3, s3, 0
	s_add_u32 s2, s2, 0x80000
	s_addc_u32 s3, s3, 0
	s_add_u32 s2, s2, 0x80000
	s_addc_u32 s3, s3, 0
	s_add_u32 s2, s2, 0x80000
	s_addc_u32 s3, s3, 0
	s_add_u32 s2, s2, 0x80000
	s_addc_u32 s3, s3, 0
	s_add_u32 s2, s2, 0x80000
	s_addc_u32 s3, s3, 0
	s_add_u32 s2, s2, 0x80000
	s_addc_u32 s3, s3, 0
	s_add_u32 s2, s2, 0x80000
	s_addc_u32 s3, s3, 0
	s_add_u32 s2, s2, 0x80000
	s_addc_u32 s3, s3, 0
	s_add_u32 s2, s2, 0x80000
	s_addc_u32 s3, s3, 0
	s_add_u32 s2, s2, 0x80000
	s_addc_u32 s3, s3, 0
	s_add_u32 s2, s2, 0x80000
	s_addc_u32 s3, s3, 0
	s_add_u32 s2, s2, 0x80000
	s_addc_u32 s3, s3, 0
	s_add_u32 s2, s2, 0x80000
	s_addc_u32 s3, s3, 0
	s_add_u32 s2, s2, 0x80000
	s_addc_u32 s3, s3, 0
	global_load_dword v174, v4, s[2:3]
	s_add_u32 s2, s2, 0x80000
	s_addc_u32 s3, s3, 0
	global_load_dword v175, v4, s[2:3]
	s_add_u32 s2, s2, 0x80000
	s_addc_u32 s3, s3, 0
	global_load_dword v195, v4, s[2:3]
	s_add_u32 s2, s2, 0x80000
	s_addc_u32 s3, s3, 0
	global_load_dword v197, v4, s[2:3]
	s_add_u32 s2, s2, 0x80000
	s_addc_u32 s3, s3, 0
	s_add_u32 s2, s2, 0x80000
	s_addc_u32 s3, s3, 0
	s_waitcnt vmcnt(0)
	v_readlane_b32 s0, v2, 0
	v_readlane_b32 s1, v2, 1
	v_readlane_b32 s4, v2, 4
	v_readlane_b32 s5, v2, 5
	v_readlane_b32 s6, v2, 6
	v_readlane_b32 s14, v2, 14
	v_readlane_b32 s20, v2, 20
	v_readlane_b32 s27, v2, 27
	v_readlane_b32 s34, v2, 34
	v_readlane_b32 s61, v2, 61
	v_readlane_b32 s70, v3, 6
	v_readlane_b32 s71, v3, 7
	v_readlane_b32 s89, v3, 25
	s_nop 4
	s_branch .LBB0_361

.LBB0_1069:
	v_readlane_b32 s52, v254, 10
	s_cmp_lt_i32 s52, 4
	s_cselect_b64 s[2:3], -1, 0
	s_and_b64 s[20:21], s[2:3], s[0:1]
	v_readlane_b32 s53, v254, 11
	v_readlane_b32 s54, v254, 12
	s_andn2_b64 vcc, exec, s[20:21]
	v_readlane_b32 s55, v254, 13
	s_cbranch_vccnz .LBB0_1396
	s_bitcmp0_b32 s54, 0
	s_cselect_b64 s[0:1], -1, 0
	s_cmpk_gt_i32 s97, 0x49f
	s_cselect_b64 s[2:3], -1, 0
	s_or_b64 s[0:1], s[0:1], s[2:3]
	s_mov_b32 s61, 0
	s_and_b64 vcc, exec, s[0:1]
	s_cbranch_vccnz .LBB0_1147
	s_add_i32 s0, s97, 0x360
	v_and_b32_e32 v146, 48, v1
	v_mov_b32_e32 v147, 0
	s_add_u32 s24, s76, 0x26200000
	v_lshl_add_u64 v[2:3], s[76:77], 0, v[146:147]
	s_mov_b64 s[2:3], 0x500000
	s_addc_u32 s25, s77, 0
	s_movk_i32 s1, 0x200
	v_lshl_add_u64 v[148:149], v[2:3], 0, s[2:3]
	v_lshrrev_b32_e32 v2, 3, v0
	v_lshlrev_b32_e32 v3, 4, v0
	v_cmp_gt_u32_e64 s[8:9], s1, v0
	s_movk_i32 s1, 0x210
	s_add_u32 s37, s76, 0x300000
	v_and_b32_e32 v161, 0x70, v3
	v_mad_u32_u24 v3, v2, s1, 0
	s_addc_u32 s44, s77, 0
	s_ashr_i32 s1, s0, 31
	s_lshl_b64 s[14:15], s[60:61], 12
	s_lshl_b64 s[16:17], s[0:1], 15
	v_add_u32_e32 v162, -3, v2
	v_add_u32_e32 v163, -2, v2
	v_add_u32_e32 v164, -1, v2
	v_cndmask_b32_e64 v165, 0, v2, s[8:9]
	v_lshlrev_b32_e32 v2, 8, v2
	s_add_u32 s1, s16, s14
	v_sub_u32_e32 v2, v3, v2
	s_addc_u32 s15, s17, s15
	v_lshl_add_u32 v167, v161, 1, v2
	v_or_b32_e32 v2, 48, v1
	s_add_u32 s14, s76, s1
	v_add_u32_e32 v6, 0, v146
	v_mul_u32_u24_e32 v7, 0x110, v2
	v_and_b32_e32 v2, 16, v0
	v_lshlrev_b32_e32 v146, 4, v1
	s_addc_u32 s15, s77, s15
	v_and_b32_e32 v4, 15, v0
	v_lshl_add_u32 v166, v161, 2, v3
	v_cmp_eq_u32_e64 s[10:11], 0, v2
	v_lshl_add_u64 v[2:3], s[14:15], 0, v[146:147]
	s_mov_b64 s[14:15], 0x44b00800
	v_lshrrev_b32_e32 v5, 4, v1
	v_lshl_or_b32 v160, s60, 4, v4
	v_lshl_add_u64 v[154:155], v[2:3], 0, s[14:15]
	v_cndmask_b32_e64 v150, 0, 1.0, s[8:9]
	v_mul_u32_u24_e32 v4, 0x110, v4
	v_lshl_add_u32 v8, v160, 2, 0
	v_mul_u32_u24_e32 v5, 0x840, v5
	s_ashr_i32 s97, s96, 31
	s_mov_b32 s38, 0x3e2aaaab
	v_mbcnt_lo_u32_b32 v2, -1, 0
	v_cmp_lt_u32_e64 s[2:3], 23, v0
	v_cmp_lt_u32_e64 s[4:5], 15, v0
	v_cmp_lt_u32_e64 s[6:7], 7, v0
	v_mov_b32_e32 v151, v150
	v_mov_b32_e32 v152, v150
	v_mov_b32_e32 v153, v150
	v_cmp_gt_u32_e64 s[12:13], 16, v1
	s_lshl_b64 s[26:27], s[96:97], 15
	v_readlane_b32 s97, v254, 60
	s_mov_b64 s[28:29], 0x2000
	s_movk_i32 s1, 0x2000
	s_mov_b64 s[30:31], 0x4000
	s_movk_i32 s45, 0x4000
	s_mov_b64 s[34:35], 0x6000
	v_add_u32_e32 v168, v6, v4
	v_add_u32_e32 v169, v6, v7
	s_mov_b32 s46, 0x3f2aaaab
	v_mov_b32_e32 v170, 0x3ecc95a3
	s_mov_b32 s47, 0x3f317218
	s_mov_b32 s48, 0x7f800000
	s_mov_b32 s49, 0x33800000
	s_mov_b32 s50, 0xbe800000
	s_mov_b32 s39, 0x3e124925
	v_mov_b32_e32 v156, 0x3f317218
	v_mov_b32_e32 v171, 0x7f800000
	v_mov_b32_e32 v172, 0x7fc00000
	v_mov_b32_e32 v173, 0xff800000
	v_add_u32_e32 v174, v8, v5
	v_mbcnt_hi_u32_b32 v175, -1, v2
	s_branch .LBB0_1073
